# P1 epilogue stores sc1 (write-through publish) on top of x loads nt
# baseline (speedup 1.0000x reference)
.LBB0_110:
	v_mov_b32_e32 v133, v136
	s_lshl_b32 s28, s68, 8
	v_readfirstlane_b32 s8, v133
	s_and_b32 s9, s8, 0xc0
	s_ashr_i32 s8, s8, 2
	s_andn2_b32 s8, s8, 63
	s_add_i32 s8, s8, s28
	v_and_or_b32 v132, v133, 15, s8
	s_lshl_b32 s8, s97, 8
	s_or_b32 s8, s9, s8
	v_lshrrev_b32_e32 v133, 1, v133
	v_and_or_b32 v134, v133, 24, s8
	v_ashrrev_i32_e32 v133, 31, v132
	v_ashrrev_i32_e32 v135, 31, v134
	v_lshlrev_b64 v[142:143], 11, v[132:133]
	v_lshl_add_u64 v[142:143], s[14:15], 0, v[142:143]
	v_lshlrev_b64 v[134:135], 1, v[134:135]
	v_lshl_add_u64 v[142:143], v[142:143], 0, v[134:135]
	v_cvt_pk_bf16_f32 v112, v112, v113
	v_cvt_pk_bf16_f32 v113, v114, v115
	v_cvt_pk_bf16_f32 v114, v116, v117
	v_cvt_pk_bf16_f32 v115, v118, v119
	global_store_dwordx4 v[142:143], v[112:115], off sc1
	v_cvt_pk_bf16_f32 v88, v88, v89
	v_cvt_pk_bf16_f32 v89, v90, v91
	v_cvt_pk_bf16_f32 v112, v120, v121
	v_cvt_pk_bf16_f32 v113, v122, v123
	v_cvt_pk_bf16_f32 v114, v124, v125
	v_cvt_pk_bf16_f32 v115, v126, v127
	global_store_dwordx4 v[142:143], v[112:115], off offset:64 sc1
	v_cvt_pk_bf16_f32 v90, v92, v93
	v_cvt_pk_bf16_f32 v91, v94, v95
	v_or_b32_e32 v112, 16, v132
	v_ashrrev_i32_e32 v113, 31, v112
	v_lshlrev_b64 v[112:113], 11, v[112:113]
	v_lshl_add_u64 v[112:113], s[14:15], 0, v[112:113]
	v_lshl_add_u64 v[112:113], v[112:113], 0, v[134:135]
	global_store_dwordx4 v[112:113], v[88:91], off sc1
	v_cvt_pk_bf16_f32 v56, v56, v57
	v_cvt_pk_bf16_f32 v57, v58, v59
	v_cvt_pk_bf16_f32 v88, v104, v105
	v_cvt_pk_bf16_f32 v89, v106, v107
	v_cvt_pk_bf16_f32 v90, v108, v109
	v_cvt_pk_bf16_f32 v91, v110, v111
	global_store_dwordx4 v[112:113], v[88:91], off offset:64 sc1
	v_cvt_pk_bf16_f32 v58, v60, v61
	v_cvt_pk_bf16_f32 v59, v62, v63
	v_or_b32_e32 v88, 32, v132
	v_ashrrev_i32_e32 v89, 31, v88
	v_lshlrev_b64 v[88:89], 11, v[88:89]
	v_lshl_add_u64 v[88:89], s[14:15], 0, v[88:89]
	v_lshl_add_u64 v[88:89], v[88:89], 0, v[134:135]
	global_store_dwordx4 v[88:89], v[56:59], off sc1
	v_cvt_pk_bf16_f32 v16, v16, v17
	v_cvt_pk_bf16_f32 v17, v18, v19
	v_cvt_pk_bf16_f32 v56, v72, v73
	v_cvt_pk_bf16_f32 v57, v74, v75
	v_cvt_pk_bf16_f32 v58, v76, v77
	v_cvt_pk_bf16_f32 v59, v78, v79
	global_store_dwordx4 v[88:89], v[56:59], off offset:64 sc1
	v_cvt_pk_bf16_f32 v18, v20, v21
	v_cvt_pk_bf16_f32 v19, v22, v23
	v_or_b32_e32 v56, 48, v132
	v_ashrrev_i32_e32 v57, 31, v56
	v_lshlrev_b64 v[56:57], 11, v[56:57]
	v_lshl_add_u64 v[56:57], s[14:15], 0, v[56:57]
	v_lshl_add_u64 v[56:57], v[56:57], 0, v[134:135]
	s_mov_b32 s8, 0x40000
	global_store_dwordx4 v[56:57], v[16:19], off sc1
	v_add_co_u32_e32 v22, vcc, s8, v142
	s_nop 0
	v_cvt_pk_bf16_f32 v16, v40, v41
	v_cvt_pk_bf16_f32 v17, v42, v43
	v_cvt_pk_bf16_f32 v18, v44, v45
	v_cvt_pk_bf16_f32 v19, v46, v47
	global_store_dwordx4 v[56:57], v[16:19], off offset:64 sc1
	s_mov_b64 s[28:29], 0x40000
	v_addc_co_u32_e32 v23, vcc, 0, v143, vcc
	v_cvt_pk_bf16_f32 v16, v80, v81
	v_cvt_pk_bf16_f32 v17, v82, v83
	v_cvt_pk_bf16_f32 v18, v84, v85
	v_cvt_pk_bf16_f32 v19, v86, v87
	v_lshl_add_u64 v[20:21], v[142:143], 0, s[28:29]
	global_store_dwordx4 v[22:23], v[16:19], off sc1
	v_add_co_u32_e32 v22, vcc, s94, v142
	s_nop 0
	v_cvt_pk_bf16_f32 v16, v96, v97
	v_cvt_pk_bf16_f32 v17, v98, v99
	v_cvt_pk_bf16_f32 v18, v100, v101
	v_cvt_pk_bf16_f32 v19, v102, v103
	global_store_dwordx4 v[20:21], v[16:19], off offset:64 sc1
	v_addc_co_u32_e32 v23, vcc, 0, v143, vcc
	s_nop 0
	v_cvt_pk_bf16_f32 v16, v48, v49
	v_cvt_pk_bf16_f32 v17, v50, v51
	v_cvt_pk_bf16_f32 v18, v52, v53
	v_cvt_pk_bf16_f32 v19, v54, v55
	s_mov_b64 s[28:29], 0x48000
	global_store_dwordx4 v[22:23], v[16:19], off sc1
	v_add_co_u32_e32 v22, vcc, s95, v142
	v_lshl_add_u64 v[20:21], v[142:143], 0, s[28:29]
	v_cvt_pk_bf16_f32 v16, v64, v65
	v_cvt_pk_bf16_f32 v17, v66, v67
	v_cvt_pk_bf16_f32 v18, v68, v69
	v_cvt_pk_bf16_f32 v19, v70, v71
	v_addc_co_u32_e32 v23, vcc, 0, v143, vcc
	global_store_dwordx4 v[20:21], v[16:19], off offset:64 sc1
	v_cvt_pk_bf16_f32 v0, v0, v1
	v_cvt_pk_bf16_f32 v1, v2, v3
	v_cvt_pk_bf16_f32 v16, v24, v25
	v_cvt_pk_bf16_f32 v17, v26, v27
	v_cvt_pk_bf16_f32 v18, v28, v29
	v_cvt_pk_bf16_f32 v19, v30, v31
	v_cvt_pk_bf16_f32 v2, v4, v5
	v_add_co_u32_e32 v4, vcc, s96, v142
	v_lshl_add_u64 v[20:21], v[142:143], 0, s[60:61]
	global_store_dwordx4 v[22:23], v[16:19], off sc1
	v_cvt_pk_bf16_f32 v3, v6, v7
	v_addc_co_u32_e32 v5, vcc, 0, v143, vcc
	v_cvt_pk_bf16_f32 v16, v32, v33
	v_cvt_pk_bf16_f32 v17, v34, v35
	v_cvt_pk_bf16_f32 v18, v36, v37
	v_cvt_pk_bf16_f32 v19, v38, v39
	global_store_dwordx4 v[20:21], v[16:19], off offset:64 sc1
	global_store_dwordx4 v[4:5], v[0:3], off sc1
	s_andn2_b64 vcc, exec, s[0:1]
	v_lshl_add_u64 v[16:17], v[142:143], 0, s[62:63]
	v_cvt_pk_bf16_f32 v0, v8, v9
	v_cvt_pk_bf16_f32 v1, v10, v11
	v_cvt_pk_bf16_f32 v2, v12, v13
	v_cvt_pk_bf16_f32 v3, v14, v15
	s_mov_b64 s[0:1], -1
	global_store_dwordx4 v[16:17], v[0:3], off offset:64 sc1
	s_cbranch_vccnz .LBB0_101
	s_andn2_b64 vcc, exec, s[16:17]
	s_cbranch_vccnz .LBB0_100
	s_barrier
	s_branch .LBB0_100

.LBB0_154:
	s_add_u32 s8, s52, s89
	s_addc_u32 s9, s53, 0
	s_ashr_i32 s5, s4, 31
	s_lshl_b64 s[4:5], s[4:5], 1
	s_add_u32 s4, s8, s4
	s_addc_u32 s5, s9, s5
	v_lshlrev_b32_e32 v148, 4, v158
	v_and_b32_e32 v142, 0x1fcf, v169
	v_lshl_add_u64 v[136:137], s[4:5], 0, v[148:149]
	s_ashr_i32 s4, s59, 13
	s_mul_hi_i32 s5, s68, s4
	s_mul_i32 s4, s68, s4
	v_mul_u32_u24_e32 v140, s66, v142
	v_lshl_add_u64 v[138:139], s[4:5], 1, v[136:137]
	v_lshlrev_b32_e32 v148, 1, v140
	v_lshl_add_u64 v[140:141], v[138:139], 0, v[148:149]
	v_cvt_pk_bf16_f32 v128, v128, v129
	v_cvt_pk_bf16_f32 v129, v130, v131
	v_cvt_pk_bf16_f32 v130, v132, v133
	v_cvt_pk_bf16_f32 v131, v134, v135
	global_store_dwordx4 v[140:141], v[128:131], off sc1
	v_mov_b64_e32 v[134:135], v[110:111]
	s_andn2_b64 vcc, exec, s[70:71]
	v_cndmask_b32_e64 v128, 0, 1, s[70:71]
	v_cmp_ne_u32_e64 s[4:5], 1, v128
	v_mov_b64_e32 v[130:131], v[118:119]
	v_mov_b64_e32 v[128:129], v[116:117]
	v_mov_b64_e32 v[132:133], v[108:109]
	s_cbranch_vccnz .LBB0_156
	v_mul_f32_e32 v128, 0xbfb8aa3b, v116
	v_mul_f32_e32 v129, 0xbfb8aa3b, v117
	v_mul_f32_e32 v130, 0xbfb8aa3b, v118
	v_mul_f32_e32 v131, 0xbfb8aa3b, v119
	v_mul_f32_e32 v132, 0xbfb8aa3b, v108
	v_mul_f32_e32 v133, 0xbfb8aa3b, v109
	v_mul_f32_e32 v134, 0xbfb8aa3b, v110
	v_mul_f32_e32 v135, 0xbfb8aa3b, v111
	v_exp_f32_e32 v128, v128
	v_exp_f32_e32 v129, v129
	v_exp_f32_e32 v130, v130
	v_exp_f32_e32 v131, v131
	v_exp_f32_e32 v132, v132
	v_exp_f32_e32 v133, v133
	v_exp_f32_e32 v134, v134
	v_exp_f32_e32 v135, v135
	v_add_f32_e32 v128, 1.0, v128
	v_add_f32_e32 v129, 1.0, v129
	v_add_f32_e32 v130, 1.0, v130
	v_add_f32_e32 v131, 1.0, v131
	v_add_f32_e32 v132, 1.0, v132
	v_add_f32_e32 v133, 1.0, v133
	v_add_f32_e32 v134, 1.0, v134
	v_add_f32_e32 v135, 1.0, v135
	v_rcp_f32_e32 v128, v128
	v_rcp_f32_e32 v129, v129
	v_rcp_f32_e32 v130, v130
	v_rcp_f32_e32 v131, v131
	v_rcp_f32_e32 v132, v132
	v_rcp_f32_e32 v134, v134
	v_rcp_f32_e32 v135, v135
	v_rcp_f32_e32 v133, v133
	v_pk_mul_f32 v[130:131], v[118:119], v[130:131]
	v_pk_mul_f32 v[128:129], v[116:117], v[128:129]
	v_pk_mul_f32 v[134:135], v[110:111], v[134:135]
	v_pk_mul_f32 v[132:133], v[108:109], v[132:133]
.LBB0_156:
	v_cvt_pk_bf16_f32 v128, v128, v129
	v_cvt_pk_bf16_f32 v129, v130, v131
	v_cvt_pk_bf16_f32 v130, v132, v133
	v_cvt_pk_bf16_f32 v131, v134, v135
	global_store_dwordx4 v[140:141], v[128:131], off offset:64 sc1
	v_mov_b64_e32 v[134:135], v[106:107]
	s_and_b64 vcc, exec, s[4:5]
	v_mov_b64_e32 v[130:131], v[114:115]
	v_mov_b64_e32 v[128:129], v[112:113]
	v_mov_b64_e32 v[132:133], v[104:105]
	s_cbranch_vccnz .LBB0_158
	v_mul_f32_e32 v128, 0xbfb8aa3b, v112
	v_mul_f32_e32 v129, 0xbfb8aa3b, v113
	v_mul_f32_e32 v130, 0xbfb8aa3b, v114
	v_mul_f32_e32 v131, 0xbfb8aa3b, v115
	v_mul_f32_e32 v132, 0xbfb8aa3b, v104
	v_mul_f32_e32 v133, 0xbfb8aa3b, v105
	v_mul_f32_e32 v134, 0xbfb8aa3b, v106
	v_mul_f32_e32 v135, 0xbfb8aa3b, v107
	v_exp_f32_e32 v128, v128
	v_exp_f32_e32 v129, v129
	v_exp_f32_e32 v130, v130
	v_exp_f32_e32 v131, v131
	v_exp_f32_e32 v132, v132
	v_exp_f32_e32 v133, v133
	v_exp_f32_e32 v134, v134
	v_exp_f32_e32 v135, v135
	v_add_f32_e32 v128, 1.0, v128
	v_add_f32_e32 v129, 1.0, v129
	v_add_f32_e32 v130, 1.0, v130
	v_add_f32_e32 v131, 1.0, v131
	v_add_f32_e32 v132, 1.0, v132
	v_add_f32_e32 v133, 1.0, v133
	v_add_f32_e32 v134, 1.0, v134
	v_add_f32_e32 v135, 1.0, v135
	v_rcp_f32_e32 v128, v128
	v_rcp_f32_e32 v129, v129
	v_rcp_f32_e32 v130, v130
	v_rcp_f32_e32 v131, v131
	v_rcp_f32_e32 v132, v132
	v_rcp_f32_e32 v134, v134
	v_rcp_f32_e32 v135, v135
	v_rcp_f32_e32 v133, v133
	v_pk_mul_f32 v[130:131], v[114:115], v[130:131]
	v_pk_mul_f32 v[128:129], v[112:113], v[128:129]
	v_pk_mul_f32 v[134:135], v[106:107], v[134:135]
	v_pk_mul_f32 v[132:133], v[104:105], v[132:133]
.LBB0_158:
	v_or_b32_e32 v140, 16, v142
	v_mul_u32_u24_e32 v140, s66, v140
	v_lshlrev_b32_e32 v148, 1, v140
	v_lshl_add_u64 v[140:141], v[138:139], 0, v[148:149]
	v_cvt_pk_bf16_f32 v128, v128, v129
	v_cvt_pk_bf16_f32 v129, v130, v131
	v_cvt_pk_bf16_f32 v130, v132, v133
	v_cvt_pk_bf16_f32 v131, v134, v135
	global_store_dwordx4 v[140:141], v[128:131], off sc1
	v_mov_b64_e32 v[134:135], v[94:95]
	s_and_b64 vcc, exec, s[4:5]
	v_mov_b64_e32 v[130:131], v[102:103]
	v_mov_b64_e32 v[128:129], v[100:101]
	v_mov_b64_e32 v[132:133], v[92:93]
	s_cbranch_vccnz .LBB0_160
	v_mul_f32_e32 v128, 0xbfb8aa3b, v100
	v_mul_f32_e32 v129, 0xbfb8aa3b, v101
	v_mul_f32_e32 v130, 0xbfb8aa3b, v102
	v_mul_f32_e32 v131, 0xbfb8aa3b, v103
	v_mul_f32_e32 v132, 0xbfb8aa3b, v92
	v_mul_f32_e32 v133, 0xbfb8aa3b, v93
	v_mul_f32_e32 v134, 0xbfb8aa3b, v94
	v_mul_f32_e32 v135, 0xbfb8aa3b, v95
	v_exp_f32_e32 v128, v128
	v_exp_f32_e32 v129, v129
	v_exp_f32_e32 v130, v130
	v_exp_f32_e32 v131, v131
	v_exp_f32_e32 v132, v132
	v_exp_f32_e32 v133, v133
	v_exp_f32_e32 v134, v134
	v_exp_f32_e32 v135, v135
	v_add_f32_e32 v128, 1.0, v128
	v_add_f32_e32 v129, 1.0, v129
	v_add_f32_e32 v130, 1.0, v130
	v_add_f32_e32 v131, 1.0, v131
	v_add_f32_e32 v132, 1.0, v132
	v_add_f32_e32 v133, 1.0, v133
	v_add_f32_e32 v134, 1.0, v134
	v_add_f32_e32 v135, 1.0, v135
	v_rcp_f32_e32 v128, v128
	v_rcp_f32_e32 v129, v129
	v_rcp_f32_e32 v130, v130
	v_rcp_f32_e32 v131, v131
	v_rcp_f32_e32 v132, v132
	v_rcp_f32_e32 v134, v134
	v_rcp_f32_e32 v135, v135
	v_rcp_f32_e32 v133, v133
	v_pk_mul_f32 v[130:131], v[102:103], v[130:131]
	v_pk_mul_f32 v[128:129], v[100:101], v[128:129]
	v_pk_mul_f32 v[134:135], v[94:95], v[134:135]
	v_pk_mul_f32 v[132:133], v[92:93], v[132:133]
.LBB0_160:
	v_cvt_pk_bf16_f32 v128, v128, v129
	v_cvt_pk_bf16_f32 v129, v130, v131
	v_cvt_pk_bf16_f32 v130, v132, v133
	v_cvt_pk_bf16_f32 v131, v134, v135
	global_store_dwordx4 v[140:141], v[128:131], off offset:64 sc1
	v_mov_b64_e32 v[134:135], v[90:91]
	s_and_b64 vcc, exec, s[4:5]
	v_mov_b64_e32 v[130:131], v[98:99]
	v_mov_b64_e32 v[128:129], v[96:97]
	v_mov_b64_e32 v[132:133], v[88:89]
	s_cbranch_vccnz .LBB0_162
	v_mul_f32_e32 v128, 0xbfb8aa3b, v96
	v_mul_f32_e32 v129, 0xbfb8aa3b, v97
	v_mul_f32_e32 v130, 0xbfb8aa3b, v98
	v_mul_f32_e32 v131, 0xbfb8aa3b, v99
	v_mul_f32_e32 v132, 0xbfb8aa3b, v88
	v_mul_f32_e32 v133, 0xbfb8aa3b, v89
	v_mul_f32_e32 v134, 0xbfb8aa3b, v90
	v_mul_f32_e32 v135, 0xbfb8aa3b, v91
	v_exp_f32_e32 v128, v128
	v_exp_f32_e32 v129, v129
	v_exp_f32_e32 v130, v130
	v_exp_f32_e32 v131, v131
	v_exp_f32_e32 v132, v132
	v_exp_f32_e32 v133, v133
	v_exp_f32_e32 v134, v134
	v_exp_f32_e32 v135, v135
	v_add_f32_e32 v128, 1.0, v128
	v_add_f32_e32 v129, 1.0, v129
	v_add_f32_e32 v130, 1.0, v130
	v_add_f32_e32 v131, 1.0, v131
	v_add_f32_e32 v132, 1.0, v132
	v_add_f32_e32 v133, 1.0, v133
	v_add_f32_e32 v134, 1.0, v134
	v_add_f32_e32 v135, 1.0, v135
	v_rcp_f32_e32 v128, v128
	v_rcp_f32_e32 v129, v129
	v_rcp_f32_e32 v130, v130
	v_rcp_f32_e32 v131, v131
	v_rcp_f32_e32 v132, v132
	v_rcp_f32_e32 v134, v134
	v_rcp_f32_e32 v135, v135
	v_rcp_f32_e32 v133, v133
	v_pk_mul_f32 v[130:131], v[98:99], v[130:131]
	v_pk_mul_f32 v[128:129], v[96:97], v[128:129]
	v_pk_mul_f32 v[134:135], v[90:91], v[134:135]
	v_pk_mul_f32 v[132:133], v[88:89], v[132:133]
.LBB0_162:
	v_or_b32_e32 v140, 32, v142
	v_mul_u32_u24_e32 v140, s66, v140
	v_lshlrev_b32_e32 v148, 1, v140
	v_lshl_add_u64 v[140:141], v[138:139], 0, v[148:149]
	v_cvt_pk_bf16_f32 v128, v128, v129
	v_cvt_pk_bf16_f32 v129, v130, v131
	v_cvt_pk_bf16_f32 v130, v132, v133
	v_cvt_pk_bf16_f32 v131, v134, v135
	global_store_dwordx4 v[140:141], v[128:131], off sc1
	v_mov_b64_e32 v[134:135], v[78:79]
	s_and_b64 vcc, exec, s[4:5]
	v_mov_b64_e32 v[130:131], v[86:87]
	v_mov_b64_e32 v[128:129], v[84:85]
	v_mov_b64_e32 v[132:133], v[76:77]
	s_cbranch_vccnz .LBB0_164
	v_mul_f32_e32 v128, 0xbfb8aa3b, v84
	v_mul_f32_e32 v129, 0xbfb8aa3b, v85
	v_mul_f32_e32 v130, 0xbfb8aa3b, v86
	v_mul_f32_e32 v131, 0xbfb8aa3b, v87
	v_mul_f32_e32 v132, 0xbfb8aa3b, v76
	v_mul_f32_e32 v133, 0xbfb8aa3b, v77
	v_mul_f32_e32 v134, 0xbfb8aa3b, v78
	v_mul_f32_e32 v135, 0xbfb8aa3b, v79
	v_exp_f32_e32 v128, v128
	v_exp_f32_e32 v129, v129
	v_exp_f32_e32 v130, v130
	v_exp_f32_e32 v131, v131
	v_exp_f32_e32 v132, v132
	v_exp_f32_e32 v133, v133
	v_exp_f32_e32 v134, v134
	v_exp_f32_e32 v135, v135
	v_add_f32_e32 v128, 1.0, v128
	v_add_f32_e32 v129, 1.0, v129
	v_add_f32_e32 v130, 1.0, v130
	v_add_f32_e32 v131, 1.0, v131
	v_add_f32_e32 v132, 1.0, v132
	v_add_f32_e32 v133, 1.0, v133
	v_add_f32_e32 v134, 1.0, v134
	v_add_f32_e32 v135, 1.0, v135
	v_rcp_f32_e32 v128, v128
	v_rcp_f32_e32 v129, v129
	v_rcp_f32_e32 v130, v130
	v_rcp_f32_e32 v131, v131
	v_rcp_f32_e32 v132, v132
	v_rcp_f32_e32 v134, v134
	v_rcp_f32_e32 v135, v135
	v_rcp_f32_e32 v133, v133
	v_pk_mul_f32 v[130:131], v[86:87], v[130:131]
	v_pk_mul_f32 v[128:129], v[84:85], v[128:129]
	v_pk_mul_f32 v[134:135], v[78:79], v[134:135]
	v_pk_mul_f32 v[132:133], v[76:77], v[132:133]
.LBB0_164:
	v_cvt_pk_bf16_f32 v128, v128, v129
	v_cvt_pk_bf16_f32 v129, v130, v131
	v_cvt_pk_bf16_f32 v130, v132, v133
	v_cvt_pk_bf16_f32 v131, v134, v135
	global_store_dwordx4 v[140:141], v[128:131], off offset:64 sc1
	v_mov_b64_e32 v[134:135], v[74:75]
	s_and_b64 vcc, exec, s[4:5]
	v_mov_b64_e32 v[130:131], v[82:83]
	v_mov_b64_e32 v[128:129], v[80:81]
	v_mov_b64_e32 v[132:133], v[72:73]
	s_cbranch_vccnz .LBB0_166
	v_mul_f32_e32 v128, 0xbfb8aa3b, v80
	v_mul_f32_e32 v129, 0xbfb8aa3b, v81
	v_mul_f32_e32 v130, 0xbfb8aa3b, v82
	v_mul_f32_e32 v131, 0xbfb8aa3b, v83
	v_mul_f32_e32 v132, 0xbfb8aa3b, v72
	v_mul_f32_e32 v133, 0xbfb8aa3b, v73
	v_mul_f32_e32 v134, 0xbfb8aa3b, v74
	v_mul_f32_e32 v135, 0xbfb8aa3b, v75
	v_exp_f32_e32 v128, v128
	v_exp_f32_e32 v129, v129
	v_exp_f32_e32 v130, v130
	v_exp_f32_e32 v131, v131
	v_exp_f32_e32 v132, v132
	v_exp_f32_e32 v133, v133
	v_exp_f32_e32 v134, v134
	v_exp_f32_e32 v135, v135
	v_add_f32_e32 v128, 1.0, v128
	v_add_f32_e32 v129, 1.0, v129
	v_add_f32_e32 v130, 1.0, v130
	v_add_f32_e32 v131, 1.0, v131
	v_add_f32_e32 v132, 1.0, v132
	v_add_f32_e32 v133, 1.0, v133
	v_add_f32_e32 v134, 1.0, v134
	v_add_f32_e32 v135, 1.0, v135
	v_rcp_f32_e32 v128, v128
	v_rcp_f32_e32 v129, v129
	v_rcp_f32_e32 v130, v130
	v_rcp_f32_e32 v131, v131
	v_rcp_f32_e32 v132, v132
	v_rcp_f32_e32 v134, v134
	v_rcp_f32_e32 v135, v135
	v_rcp_f32_e32 v133, v133
	v_pk_mul_f32 v[130:131], v[82:83], v[130:131]
	v_pk_mul_f32 v[128:129], v[80:81], v[128:129]
	v_pk_mul_f32 v[134:135], v[74:75], v[134:135]
	v_pk_mul_f32 v[132:133], v[72:73], v[132:133]
.LBB0_166:
	v_or_b32_e32 v140, 48, v142
	v_mul_u32_u24_e32 v140, s66, v140
	v_lshlrev_b32_e32 v148, 1, v140
	v_lshl_add_u64 v[138:139], v[138:139], 0, v[148:149]
	v_cvt_pk_bf16_f32 v128, v128, v129
	v_cvt_pk_bf16_f32 v129, v130, v131
	v_cvt_pk_bf16_f32 v130, v132, v133
	v_cvt_pk_bf16_f32 v131, v134, v135
	global_store_dwordx4 v[138:139], v[128:131], off sc1
	v_mov_b64_e32 v[134:135], v[66:67]
	s_and_b64 vcc, exec, s[4:5]
	v_mov_b64_e32 v[130:131], v[70:71]
	v_mov_b64_e32 v[128:129], v[68:69]
	v_mov_b64_e32 v[132:133], v[64:65]
	s_cbranch_vccnz .LBB0_168
	v_mul_f32_e32 v128, 0xbfb8aa3b, v68
	v_mul_f32_e32 v129, 0xbfb8aa3b, v69
	v_mul_f32_e32 v130, 0xbfb8aa3b, v70
	v_mul_f32_e32 v131, 0xbfb8aa3b, v71
	v_mul_f32_e32 v132, 0xbfb8aa3b, v64
	v_mul_f32_e32 v133, 0xbfb8aa3b, v65
	v_mul_f32_e32 v134, 0xbfb8aa3b, v66
	v_mul_f32_e32 v135, 0xbfb8aa3b, v67
	v_exp_f32_e32 v128, v128
	v_exp_f32_e32 v129, v129
	v_exp_f32_e32 v130, v130
	v_exp_f32_e32 v131, v131
	v_exp_f32_e32 v132, v132
	v_exp_f32_e32 v133, v133
	v_exp_f32_e32 v134, v134
	v_exp_f32_e32 v135, v135
	v_add_f32_e32 v128, 1.0, v128
	v_add_f32_e32 v129, 1.0, v129
	v_add_f32_e32 v130, 1.0, v130
	v_add_f32_e32 v131, 1.0, v131
	v_add_f32_e32 v132, 1.0, v132
	v_add_f32_e32 v133, 1.0, v133
	v_add_f32_e32 v134, 1.0, v134
	v_add_f32_e32 v135, 1.0, v135
	v_rcp_f32_e32 v128, v128
	v_rcp_f32_e32 v129, v129
	v_rcp_f32_e32 v130, v130
	v_rcp_f32_e32 v131, v131
	v_rcp_f32_e32 v132, v132
	v_rcp_f32_e32 v134, v134
	v_rcp_f32_e32 v135, v135
	v_rcp_f32_e32 v133, v133
	v_pk_mul_f32 v[130:131], v[70:71], v[130:131]
	v_pk_mul_f32 v[128:129], v[68:69], v[128:129]
	v_pk_mul_f32 v[134:135], v[66:67], v[134:135]
	v_pk_mul_f32 v[132:133], v[64:65], v[132:133]
.LBB0_168:
	v_cvt_pk_bf16_f32 v128, v128, v129
	v_cvt_pk_bf16_f32 v129, v130, v131
	v_cvt_pk_bf16_f32 v130, v132, v133
	v_cvt_pk_bf16_f32 v131, v134, v135
	global_store_dwordx4 v[138:139], v[128:131], off offset:64 sc1
	v_mov_b64_e32 v[134:135], v[58:59]
	s_and_b64 vcc, exec, s[4:5]
	v_mov_b64_e32 v[130:131], v[62:63]
	v_mov_b64_e32 v[128:129], v[60:61]
	v_mov_b64_e32 v[132:133], v[56:57]
	s_cbranch_vccnz .LBB0_170
	v_mul_f32_e32 v128, 0xbfb8aa3b, v60
	v_mul_f32_e32 v129, 0xbfb8aa3b, v61
	v_mul_f32_e32 v130, 0xbfb8aa3b, v62
	v_mul_f32_e32 v131, 0xbfb8aa3b, v63
	v_mul_f32_e32 v132, 0xbfb8aa3b, v56
	v_mul_f32_e32 v133, 0xbfb8aa3b, v57
	v_mul_f32_e32 v134, 0xbfb8aa3b, v58
	v_mul_f32_e32 v135, 0xbfb8aa3b, v59
	v_exp_f32_e32 v128, v128
	v_exp_f32_e32 v129, v129
	v_exp_f32_e32 v130, v130
	v_exp_f32_e32 v131, v131
	v_exp_f32_e32 v132, v132
	v_exp_f32_e32 v133, v133
	v_exp_f32_e32 v134, v134
	v_exp_f32_e32 v135, v135
	v_add_f32_e32 v128, 1.0, v128
	v_add_f32_e32 v129, 1.0, v129
	v_add_f32_e32 v130, 1.0, v130
	v_add_f32_e32 v131, 1.0, v131
	v_add_f32_e32 v132, 1.0, v132
	v_add_f32_e32 v133, 1.0, v133
	v_add_f32_e32 v134, 1.0, v134
	v_add_f32_e32 v135, 1.0, v135
	v_rcp_f32_e32 v128, v128
	v_rcp_f32_e32 v129, v129
	v_rcp_f32_e32 v130, v130
	v_rcp_f32_e32 v131, v131
	v_rcp_f32_e32 v132, v132
	v_rcp_f32_e32 v134, v134
	v_rcp_f32_e32 v135, v135
	v_rcp_f32_e32 v133, v133
	v_pk_mul_f32 v[130:131], v[62:63], v[130:131]
	v_pk_mul_f32 v[128:129], v[60:61], v[128:129]
	v_pk_mul_f32 v[134:135], v[58:59], v[134:135]
	v_pk_mul_f32 v[132:133], v[56:57], v[132:133]
.LBB0_170:
	v_add_u32_e32 v138, 0x80, v169
	v_and_b32_e32 v140, 0x1fcf, v138
	v_ashrrev_i32_e32 v138, 13, v138
	v_mad_i64_i32 v[138:139], s[28:29], s68, v138, 0
	v_lshl_add_u64 v[136:137], v[138:139], 1, v[136:137]
	v_mul_u32_u24_e32 v138, s66, v140
	v_lshlrev_b32_e32 v148, 1, v138
	v_lshl_add_u64 v[138:139], v[136:137], 0, v[148:149]
	v_cvt_pk_bf16_f32 v128, v128, v129
	v_cvt_pk_bf16_f32 v129, v130, v131
	v_cvt_pk_bf16_f32 v130, v132, v133
	v_cvt_pk_bf16_f32 v131, v134, v135
	global_store_dwordx4 v[138:139], v[128:131], off sc1
	v_mov_b64_e32 v[134:135], v[46:47]
	s_and_b64 vcc, exec, s[4:5]
	v_mov_b64_e32 v[130:131], v[54:55]
	v_mov_b64_e32 v[128:129], v[52:53]
	v_mov_b64_e32 v[132:133], v[44:45]
	s_cbranch_vccnz .LBB0_172
	v_mul_f32_e32 v128, 0xbfb8aa3b, v52
	v_mul_f32_e32 v129, 0xbfb8aa3b, v53
	v_mul_f32_e32 v130, 0xbfb8aa3b, v54
	v_mul_f32_e32 v131, 0xbfb8aa3b, v55
	v_mul_f32_e32 v132, 0xbfb8aa3b, v44
	v_mul_f32_e32 v133, 0xbfb8aa3b, v45
	v_mul_f32_e32 v134, 0xbfb8aa3b, v46
	v_mul_f32_e32 v135, 0xbfb8aa3b, v47
	v_exp_f32_e32 v128, v128
	v_exp_f32_e32 v129, v129
	v_exp_f32_e32 v130, v130
	v_exp_f32_e32 v131, v131
	v_exp_f32_e32 v132, v132
	v_exp_f32_e32 v133, v133
	v_exp_f32_e32 v134, v134
	v_exp_f32_e32 v135, v135
	v_add_f32_e32 v128, 1.0, v128
	v_add_f32_e32 v129, 1.0, v129
	v_add_f32_e32 v130, 1.0, v130
	v_add_f32_e32 v131, 1.0, v131
	v_add_f32_e32 v132, 1.0, v132
	v_add_f32_e32 v133, 1.0, v133
	v_add_f32_e32 v134, 1.0, v134
	v_add_f32_e32 v135, 1.0, v135
	v_rcp_f32_e32 v128, v128
	v_rcp_f32_e32 v129, v129
	v_rcp_f32_e32 v130, v130
	v_rcp_f32_e32 v131, v131
	v_rcp_f32_e32 v132, v132
	v_rcp_f32_e32 v134, v134
	v_rcp_f32_e32 v135, v135
	v_rcp_f32_e32 v133, v133
	v_pk_mul_f32 v[130:131], v[54:55], v[130:131]
	v_pk_mul_f32 v[128:129], v[52:53], v[128:129]
	v_pk_mul_f32 v[134:135], v[46:47], v[134:135]
	v_pk_mul_f32 v[132:133], v[44:45], v[132:133]
.LBB0_172:
	v_cvt_pk_bf16_f32 v128, v128, v129
	v_cvt_pk_bf16_f32 v129, v130, v131
	v_cvt_pk_bf16_f32 v130, v132, v133
	v_cvt_pk_bf16_f32 v131, v134, v135
	global_store_dwordx4 v[138:139], v[128:131], off offset:64 sc1
	v_mov_b64_e32 v[134:135], v[42:43]
	s_and_b64 vcc, exec, s[4:5]
	v_mov_b64_e32 v[130:131], v[50:51]
	v_mov_b64_e32 v[128:129], v[48:49]
	v_mov_b64_e32 v[132:133], v[40:41]
	s_cbranch_vccnz .LBB0_174
	v_mul_f32_e32 v128, 0xbfb8aa3b, v48
	v_mul_f32_e32 v129, 0xbfb8aa3b, v49
	v_mul_f32_e32 v130, 0xbfb8aa3b, v50
	v_mul_f32_e32 v131, 0xbfb8aa3b, v51
	v_mul_f32_e32 v132, 0xbfb8aa3b, v40
	v_mul_f32_e32 v133, 0xbfb8aa3b, v41
	v_mul_f32_e32 v134, 0xbfb8aa3b, v42
	v_mul_f32_e32 v135, 0xbfb8aa3b, v43
	v_exp_f32_e32 v128, v128
	v_exp_f32_e32 v129, v129
	v_exp_f32_e32 v130, v130
	v_exp_f32_e32 v131, v131
	v_exp_f32_e32 v132, v132
	v_exp_f32_e32 v133, v133
	v_exp_f32_e32 v134, v134
	v_exp_f32_e32 v135, v135
	v_add_f32_e32 v128, 1.0, v128
	v_add_f32_e32 v129, 1.0, v129
	v_add_f32_e32 v130, 1.0, v130
	v_add_f32_e32 v131, 1.0, v131
	v_add_f32_e32 v132, 1.0, v132
	v_add_f32_e32 v133, 1.0, v133
	v_add_f32_e32 v134, 1.0, v134
	v_add_f32_e32 v135, 1.0, v135
	v_rcp_f32_e32 v128, v128
	v_rcp_f32_e32 v129, v129
	v_rcp_f32_e32 v130, v130
	v_rcp_f32_e32 v131, v131
	v_rcp_f32_e32 v132, v132
	v_rcp_f32_e32 v134, v134
	v_rcp_f32_e32 v135, v135
	v_rcp_f32_e32 v133, v133
	v_pk_mul_f32 v[130:131], v[50:51], v[130:131]
	v_pk_mul_f32 v[128:129], v[48:49], v[128:129]
	v_pk_mul_f32 v[134:135], v[42:43], v[134:135]
	v_pk_mul_f32 v[132:133], v[40:41], v[132:133]
.LBB0_174:
	v_or_b32_e32 v138, 16, v140
	v_mul_u32_u24_e32 v138, s66, v138
	v_lshlrev_b32_e32 v148, 1, v138
	v_lshl_add_u64 v[138:139], v[136:137], 0, v[148:149]
	v_cvt_pk_bf16_f32 v128, v128, v129
	v_cvt_pk_bf16_f32 v129, v130, v131
	v_cvt_pk_bf16_f32 v130, v132, v133
	v_cvt_pk_bf16_f32 v131, v134, v135
	global_store_dwordx4 v[138:139], v[128:131], off sc1
	v_mov_b64_e32 v[134:135], v[30:31]
	s_and_b64 vcc, exec, s[4:5]
	v_mov_b64_e32 v[130:131], v[38:39]
	v_mov_b64_e32 v[128:129], v[36:37]
	v_mov_b64_e32 v[132:133], v[28:29]
	s_cbranch_vccnz .LBB0_176
	v_mul_f32_e32 v128, 0xbfb8aa3b, v36
	v_mul_f32_e32 v129, 0xbfb8aa3b, v37
	v_mul_f32_e32 v130, 0xbfb8aa3b, v38
	v_mul_f32_e32 v131, 0xbfb8aa3b, v39
	v_mul_f32_e32 v132, 0xbfb8aa3b, v28
	v_mul_f32_e32 v133, 0xbfb8aa3b, v29
	v_mul_f32_e32 v134, 0xbfb8aa3b, v30
	v_mul_f32_e32 v135, 0xbfb8aa3b, v31
	v_exp_f32_e32 v128, v128
	v_exp_f32_e32 v129, v129
	v_exp_f32_e32 v130, v130
	v_exp_f32_e32 v131, v131
	v_exp_f32_e32 v132, v132
	v_exp_f32_e32 v133, v133
	v_exp_f32_e32 v134, v134
	v_exp_f32_e32 v135, v135
	v_add_f32_e32 v128, 1.0, v128
	v_add_f32_e32 v129, 1.0, v129
	v_add_f32_e32 v130, 1.0, v130
	v_add_f32_e32 v131, 1.0, v131
	v_add_f32_e32 v132, 1.0, v132
	v_add_f32_e32 v133, 1.0, v133
	v_add_f32_e32 v134, 1.0, v134
	v_add_f32_e32 v135, 1.0, v135
	v_rcp_f32_e32 v128, v128
	v_rcp_f32_e32 v129, v129
	v_rcp_f32_e32 v130, v130
	v_rcp_f32_e32 v131, v131
	v_rcp_f32_e32 v132, v132
	v_rcp_f32_e32 v134, v134
	v_rcp_f32_e32 v135, v135
	v_rcp_f32_e32 v133, v133
	v_pk_mul_f32 v[130:131], v[38:39], v[130:131]
	v_pk_mul_f32 v[128:129], v[36:37], v[128:129]
	v_pk_mul_f32 v[134:135], v[30:31], v[134:135]
	v_pk_mul_f32 v[132:133], v[28:29], v[132:133]
.LBB0_176:
	v_cvt_pk_bf16_f32 v128, v128, v129
	v_cvt_pk_bf16_f32 v129, v130, v131
	v_cvt_pk_bf16_f32 v130, v132, v133
	v_cvt_pk_bf16_f32 v131, v134, v135
	global_store_dwordx4 v[138:139], v[128:131], off offset:64 sc1
	v_mov_b64_e32 v[134:135], v[26:27]
	s_and_b64 vcc, exec, s[4:5]
	v_mov_b64_e32 v[130:131], v[34:35]
	v_mov_b64_e32 v[128:129], v[32:33]
	v_mov_b64_e32 v[132:133], v[24:25]
	s_cbranch_vccnz .LBB0_178
	v_mul_f32_e32 v128, 0xbfb8aa3b, v32
	v_mul_f32_e32 v129, 0xbfb8aa3b, v33
	v_mul_f32_e32 v130, 0xbfb8aa3b, v34
	v_mul_f32_e32 v131, 0xbfb8aa3b, v35
	v_mul_f32_e32 v132, 0xbfb8aa3b, v24
	v_mul_f32_e32 v133, 0xbfb8aa3b, v25
	v_mul_f32_e32 v134, 0xbfb8aa3b, v26
	v_mul_f32_e32 v135, 0xbfb8aa3b, v27
	v_exp_f32_e32 v128, v128
	v_exp_f32_e32 v129, v129
	v_exp_f32_e32 v130, v130
	v_exp_f32_e32 v131, v131
	v_exp_f32_e32 v132, v132
	v_exp_f32_e32 v133, v133
	v_exp_f32_e32 v134, v134
	v_exp_f32_e32 v135, v135
	v_add_f32_e32 v128, 1.0, v128
	v_add_f32_e32 v129, 1.0, v129
	v_add_f32_e32 v130, 1.0, v130
	v_add_f32_e32 v131, 1.0, v131
	v_add_f32_e32 v132, 1.0, v132
	v_add_f32_e32 v133, 1.0, v133
	v_add_f32_e32 v134, 1.0, v134
	v_add_f32_e32 v135, 1.0, v135
	v_rcp_f32_e32 v128, v128
	v_rcp_f32_e32 v129, v129
	v_rcp_f32_e32 v130, v130
	v_rcp_f32_e32 v131, v131
	v_rcp_f32_e32 v132, v132
	v_rcp_f32_e32 v134, v134
	v_rcp_f32_e32 v135, v135
	v_rcp_f32_e32 v133, v133
	v_pk_mul_f32 v[130:131], v[34:35], v[130:131]
	v_pk_mul_f32 v[128:129], v[32:33], v[128:129]
	v_pk_mul_f32 v[134:135], v[26:27], v[134:135]
	v_pk_mul_f32 v[132:133], v[24:25], v[132:133]
.LBB0_178:
	v_or_b32_e32 v138, 32, v140
	v_mul_u32_u24_e32 v138, s66, v138
	v_lshlrev_b32_e32 v148, 1, v138
	v_lshl_add_u64 v[138:139], v[136:137], 0, v[148:149]
	v_cvt_pk_bf16_f32 v128, v128, v129
	v_cvt_pk_bf16_f32 v129, v130, v131
	v_cvt_pk_bf16_f32 v130, v132, v133
	v_cvt_pk_bf16_f32 v131, v134, v135
	global_store_dwordx4 v[138:139], v[128:131], off sc1
	v_mov_b64_e32 v[134:135], v[14:15]
	s_and_b64 vcc, exec, s[4:5]
	v_mov_b64_e32 v[130:131], v[22:23]
	v_mov_b64_e32 v[128:129], v[20:21]
	v_mov_b64_e32 v[132:133], v[12:13]
	s_cbranch_vccnz .LBB0_180
	v_mul_f32_e32 v128, 0xbfb8aa3b, v20
	v_mul_f32_e32 v129, 0xbfb8aa3b, v21
	v_mul_f32_e32 v130, 0xbfb8aa3b, v22
	v_mul_f32_e32 v131, 0xbfb8aa3b, v23
	v_mul_f32_e32 v132, 0xbfb8aa3b, v12
	v_mul_f32_e32 v133, 0xbfb8aa3b, v13
	v_mul_f32_e32 v134, 0xbfb8aa3b, v14
	v_mul_f32_e32 v135, 0xbfb8aa3b, v15
	v_exp_f32_e32 v128, v128
	v_exp_f32_e32 v129, v129
	v_exp_f32_e32 v130, v130
	v_exp_f32_e32 v131, v131
	v_exp_f32_e32 v132, v132
	v_exp_f32_e32 v133, v133
	v_exp_f32_e32 v134, v134
	v_exp_f32_e32 v135, v135
	v_add_f32_e32 v128, 1.0, v128
	v_add_f32_e32 v129, 1.0, v129
	v_add_f32_e32 v130, 1.0, v130
	v_add_f32_e32 v131, 1.0, v131
	v_add_f32_e32 v132, 1.0, v132
	v_add_f32_e32 v133, 1.0, v133
	v_add_f32_e32 v134, 1.0, v134
	v_add_f32_e32 v135, 1.0, v135
	v_rcp_f32_e32 v128, v128
	v_rcp_f32_e32 v129, v129
	v_rcp_f32_e32 v130, v130
	v_rcp_f32_e32 v131, v131
	v_rcp_f32_e32 v132, v132
	v_rcp_f32_e32 v134, v134
	v_rcp_f32_e32 v135, v135
	v_rcp_f32_e32 v133, v133
	v_pk_mul_f32 v[130:131], v[22:23], v[130:131]
	v_pk_mul_f32 v[128:129], v[20:21], v[128:129]
	v_pk_mul_f32 v[134:135], v[14:15], v[134:135]
	v_pk_mul_f32 v[132:133], v[12:13], v[132:133]
.LBB0_180:
	v_cvt_pk_bf16_f32 v128, v128, v129
	v_cvt_pk_bf16_f32 v129, v130, v131
	v_cvt_pk_bf16_f32 v130, v132, v133
	v_cvt_pk_bf16_f32 v131, v134, v135
	global_store_dwordx4 v[138:139], v[128:131], off offset:64 sc1
	v_mov_b64_e32 v[134:135], v[10:11]
	s_and_b64 vcc, exec, s[4:5]
	v_mov_b64_e32 v[130:131], v[18:19]
	v_mov_b64_e32 v[128:129], v[16:17]
	v_mov_b64_e32 v[132:133], v[8:9]
	s_cbranch_vccnz .LBB0_182
	v_mul_f32_e32 v128, 0xbfb8aa3b, v16
	v_mul_f32_e32 v129, 0xbfb8aa3b, v17
	v_mul_f32_e32 v130, 0xbfb8aa3b, v18
	v_mul_f32_e32 v131, 0xbfb8aa3b, v19
	v_mul_f32_e32 v132, 0xbfb8aa3b, v8
	v_mul_f32_e32 v133, 0xbfb8aa3b, v9
	v_mul_f32_e32 v134, 0xbfb8aa3b, v10
	v_mul_f32_e32 v135, 0xbfb8aa3b, v11
	v_exp_f32_e32 v128, v128
	v_exp_f32_e32 v129, v129
	v_exp_f32_e32 v130, v130
	v_exp_f32_e32 v131, v131
	v_exp_f32_e32 v132, v132
	v_exp_f32_e32 v133, v133
	v_exp_f32_e32 v134, v134
	v_exp_f32_e32 v135, v135
	v_add_f32_e32 v128, 1.0, v128
	v_add_f32_e32 v129, 1.0, v129
	v_add_f32_e32 v130, 1.0, v130
	v_add_f32_e32 v131, 1.0, v131
	v_add_f32_e32 v132, 1.0, v132
	v_add_f32_e32 v133, 1.0, v133
	v_add_f32_e32 v134, 1.0, v134
	v_add_f32_e32 v135, 1.0, v135
	v_rcp_f32_e32 v128, v128
	v_rcp_f32_e32 v129, v129
	v_rcp_f32_e32 v130, v130
	v_rcp_f32_e32 v131, v131
	v_rcp_f32_e32 v132, v132
	v_rcp_f32_e32 v134, v134
	v_rcp_f32_e32 v135, v135
	v_rcp_f32_e32 v133, v133
	v_pk_mul_f32 v[130:131], v[18:19], v[130:131]
	v_pk_mul_f32 v[128:129], v[16:17], v[128:129]
	v_pk_mul_f32 v[134:135], v[10:11], v[134:135]
	v_pk_mul_f32 v[132:133], v[8:9], v[132:133]
.LBB0_182:
	v_or_b32_e32 v138, 48, v140
	v_mul_u32_u24_e32 v138, s66, v138
	v_lshlrev_b32_e32 v148, 1, v138
	v_lshl_add_u64 v[136:137], v[136:137], 0, v[148:149]
	v_cvt_pk_bf16_f32 v128, v128, v129
	v_cvt_pk_bf16_f32 v129, v130, v131
	v_cvt_pk_bf16_f32 v130, v132, v133
	v_cvt_pk_bf16_f32 v131, v134, v135
	global_store_dwordx4 v[136:137], v[128:131], off sc1
	v_mov_b64_e32 v[134:135], v[2:3]
	s_and_b64 vcc, exec, s[4:5]
	v_mov_b64_e32 v[130:131], v[6:7]
	v_mov_b64_e32 v[128:129], v[4:5]
	v_mov_b64_e32 v[132:133], v[0:1]
	s_cbranch_vccnz .LBB0_184
	v_mul_f32_e32 v128, 0xbfb8aa3b, v4
	v_mul_f32_e32 v129, 0xbfb8aa3b, v5
	v_mul_f32_e32 v130, 0xbfb8aa3b, v6
	v_mul_f32_e32 v131, 0xbfb8aa3b, v7
	v_mul_f32_e32 v132, 0xbfb8aa3b, v0
	v_mul_f32_e32 v133, 0xbfb8aa3b, v1
	v_mul_f32_e32 v134, 0xbfb8aa3b, v2
	v_mul_f32_e32 v135, 0xbfb8aa3b, v3
	v_exp_f32_e32 v128, v128
	v_exp_f32_e32 v129, v129
	v_exp_f32_e32 v130, v130
	v_exp_f32_e32 v131, v131
	v_exp_f32_e32 v132, v132
	v_exp_f32_e32 v133, v133
	v_exp_f32_e32 v134, v134
	v_exp_f32_e32 v135, v135
	v_add_f32_e32 v128, 1.0, v128
	v_add_f32_e32 v129, 1.0, v129
	v_add_f32_e32 v130, 1.0, v130
	v_add_f32_e32 v131, 1.0, v131
	v_add_f32_e32 v132, 1.0, v132
	v_add_f32_e32 v133, 1.0, v133
	v_add_f32_e32 v134, 1.0, v134
	v_add_f32_e32 v135, 1.0, v135
	v_rcp_f32_e32 v128, v128
	v_rcp_f32_e32 v129, v129
	v_rcp_f32_e32 v130, v130
	v_rcp_f32_e32 v131, v131
	v_rcp_f32_e32 v132, v132
	v_rcp_f32_e32 v134, v134
	v_rcp_f32_e32 v135, v135
	v_rcp_f32_e32 v133, v133
	v_pk_mul_f32 v[130:131], v[6:7], v[130:131]
	v_pk_mul_f32 v[128:129], v[4:5], v[128:129]
	v_pk_mul_f32 v[134:135], v[2:3], v[134:135]
	v_pk_mul_f32 v[132:133], v[0:1], v[132:133]
.LBB0_184:
	v_cvt_pk_bf16_f32 v128, v128, v129
	v_cvt_pk_bf16_f32 v129, v130, v131
	v_cvt_pk_bf16_f32 v130, v132, v133
	v_cvt_pk_bf16_f32 v131, v134, v135
	global_store_dwordx4 v[136:137], v[128:131], off offset:64 sc1
	s_mov_b64 s[4:5], 0
.LBB0_185:
	s_and_b64 vcc, exec, s[4:5]
	s_cbranch_vccz .LBB0_187
	s_cmp_gt_i32 s88, 1
	s_cselect_b64 s[4:5], -1, 0
	s_cmp_lg_u64 s[4:5], 0
	s_subb_u32 s4, s88, 0
	s_lshl_b32 s4, s4, 6
	s_ashr_i32 s5, s4, 31
	s_lshl_b64 s[4:5], s[4:5], 2
	s_add_u32 s28, s76, s4
	s_addc_u32 s29, s77, s5
	v_lshlrev_b32_e32 v132, 5, v158
	global_load_dwordx4 v[136:139], v132, s[28:29] offset:16
	global_load_dwordx4 v[140:143], v132, s[28:29]
	global_load_dwordx4 v[128:131], v132, s[28:29] offset:144
	s_nop 0
	global_load_dwordx4 v[132:135], v132, s[28:29] offset:128
	v_mov_b32_e32 v172, v125
	v_mov_b32_e32 v173, v117
	v_mov_b32_e32 v160, v124
	v_mov_b32_e32 v161, v116
	v_pk_mul_f32 v[172:173], v[172:173], v[172:173]
	v_mov_b32_e32 v174, v127
	v_mov_b32_e32 v175, v119
	v_pk_fma_f32 v[160:161], v[160:161], v[160:161], v[172:173]
	v_mov_b32_e32 v172, v126
	v_mov_b32_e32 v173, v118
	v_pk_mul_f32 v[174:175], v[174:175], v[174:175]
	v_mov_b32_e32 v176, v123
	v_pk_fma_f32 v[172:173], v[172:173], v[172:173], v[174:175]
	v_mov_b32_e32 v174, v121
	v_mov_b32_e32 v175, v109
	v_pk_add_f32 v[160:161], v[160:161], v[172:173]
	v_mov_b32_e32 v172, v120
	v_mov_b32_e32 v173, v108
	v_pk_mul_f32 v[174:175], v[174:175], v[174:175]
	v_mov_b32_e32 v177, v111
	v_pk_fma_f32 v[172:173], v[172:173], v[172:173], v[174:175]
	v_mov_b32_e32 v174, v122
	v_mov_b32_e32 v175, v110
	v_pk_mul_f32 v[176:177], v[176:177], v[176:177]
	v_mov_b32_e32 v178, v107
	v_pk_fma_f32 v[174:175], v[174:175], v[174:175], v[176:177]
	v_mov_b32_e32 v176, v115
	v_pk_add_f32 v[172:173], v[172:173], v[174:175]
	v_mov_b32_e32 v174, v113
	v_mov_b32_e32 v175, v101
	v_pk_add_f32 v[160:161], v[160:161], v[172:173]
	v_mov_b32_e32 v172, v112
	v_mov_b32_e32 v173, v100
	v_pk_mul_f32 v[174:175], v[174:175], v[174:175]
	v_mov_b32_e32 v177, v103
	v_pk_fma_f32 v[172:173], v[172:173], v[172:173], v[174:175]
	v_mov_b32_e32 v174, v114
	v_mov_b32_e32 v175, v102
	v_pk_mul_f32 v[176:177], v[176:177], v[176:177]
	v_mov_b32_e32 v179, v95
	v_pk_fma_f32 v[174:175], v[174:175], v[174:175], v[176:177]
	v_mov_b32_e32 v176, v105
	v_mov_b32_e32 v177, v93
	v_pk_add_f32 v[172:173], v[172:173], v[174:175]
	v_mov_b32_e32 v174, v104
	v_mov_b32_e32 v175, v92
	v_pk_mul_f32 v[176:177], v[176:177], v[176:177]
	v_pk_mul_f32 v[178:179], v[178:179], v[178:179]
	v_pk_fma_f32 v[174:175], v[174:175], v[174:175], v[176:177]
	v_mov_b32_e32 v176, v106
	v_mov_b32_e32 v177, v94
	v_and_b32_e32 v159, 64, v168
	v_pk_fma_f32 v[176:177], v[176:177], v[176:177], v[178:179]
	v_xor_b32_e32 v148, 16, v168
	v_add_u32_e32 v159, 64, v159
	v_pk_add_f32 v[174:175], v[174:175], v[176:177]
	v_cmp_lt_i32_e32 vcc, v148, v159
	v_pk_add_f32 v[172:173], v[172:173], v[174:175]
	v_mov_b32_e32 v175, v160
	v_cndmask_b32_e32 v148, v168, v148, vcc
	v_mov_b32_e32 v174, v172
	v_mov_b32_e32 v160, v173
	v_lshlrev_b32_e32 v171, 2, v148
	v_pk_add_f32 v[172:173], v[174:175], v[160:161]
	ds_bpermute_b32 v175, v171, v173
	ds_bpermute_b32 v174, v171, v172
	v_xor_b32_e32 v148, 32, v168
	v_cmp_lt_i32_e32 vcc, v148, v159
	s_cmp_eq_u32 s88, 3
	s_cselect_b32 s4, s85, 0x7800000
	v_cndmask_b32_e32 v148, v168, v148, vcc
	v_lshlrev_b32_e32 v170, 2, v148
	v_lshlrev_b32_e32 v148, 4, v158
	s_waitcnt lgkmcnt(0)
	v_pk_add_f32 v[158:159], v[172:173], v[174:175]
	ds_bpermute_b32 v173, v170, v159
	ds_bpermute_b32 v172, v170, v158
	s_cmp_lg_u32 s88, 1
	s_cselect_b32 s8, s4, 0x4800000
	s_and_b64 s[4:5], exec, s[64:65]
	s_cselect_b32 s4, 0x3800000, s8
	s_add_u32 s4, s52, s4
	s_waitcnt lgkmcnt(0)
	v_pk_add_f32 v[172:173], v[158:159], v[172:173]
	v_mov_b64_e32 v[158:159], s[50:51]
	s_addc_u32 s5, s53, 0
	v_pk_fma_f32 v[172:173], v[172:173], s[48:49], v[158:159] op_sel_hi:[1,0,0]
	v_lshl_add_u64 v[160:161], s[4:5], 0, v[148:149]
	s_ashr_i32 s4, s59, 10
	v_mul_f32_e32 v148, 0x4b800000, v173
	v_cmp_gt_f32_e32 vcc, s86, v173
	s_and_b32 s8, s57, 7
	s_and_b32 s4, s4, -8
	v_cndmask_b32_e32 v148, v173, v148, vcc
	s_or_b32 s4, s4, s8
	v_rsq_f32_e32 v162, v148
	s_ashr_i32 s5, s4, 31
	s_lshl_b64 s[4:5], s[4:5], 20
	v_lshlrev_b32_e32 v148, 7, v169
	v_lshl_add_u64 v[174:175], v[160:161], 0, s[4:5]
	v_and_b32_e32 v148, 0xfe780, v148
	v_lshl_add_u64 v[174:175], v[174:175], 0, v[148:149]
	v_mul_f32_e32 v148, 0x45800000, v162
	v_cndmask_b32_e32 v148, v162, v148, vcc
	v_pk_mul_f32 v[124:125], v[124:125], v[148:149] op_sel_hi:[1,0]
	v_pk_mul_f32 v[126:127], v[126:127], v[148:149] op_sel_hi:[1,0]
	v_pk_mul_f32 v[120:121], v[120:121], v[148:149] op_sel_hi:[1,0]
	v_pk_mul_f32 v[122:123], v[122:123], v[148:149] op_sel_hi:[1,0]
	s_waitcnt vmcnt(0)
	v_pk_mul_f32 v[126:127], v[142:143], v[126:127]
	v_pk_mul_f32 v[124:125], v[140:141], v[124:125]
	v_pk_mul_f32 v[176:177], v[138:139], v[122:123]
	v_pk_mul_f32 v[122:123], v[136:137], v[120:121]
	v_pk_mul_f32 v[116:117], v[116:117], v[148:149] op_sel_hi:[1,0]
	v_cvt_pk_bf16_f32 v120, v124, v125
	v_cvt_pk_bf16_f32 v121, v126, v127
	v_cvt_pk_bf16_f32 v122, v122, v123
	v_cvt_pk_bf16_f32 v123, v176, v177
	v_pk_mul_f32 v[116:117], v[132:133], v[116:117]
	v_pk_mul_f32 v[108:109], v[108:109], v[148:149] op_sel_hi:[1,0]
	v_pk_mul_f32 v[110:111], v[110:111], v[148:149] op_sel_hi:[1,0]
	global_store_dwordx4 v[174:175], v[120:123], off sc1
	v_cmp_gt_f32_e32 vcc, s86, v172
	v_pk_mul_f32 v[118:119], v[118:119], v[148:149] op_sel_hi:[1,0]
	v_pk_mul_f32 v[120:121], v[130:131], v[110:111]
	v_pk_mul_f32 v[110:111], v[128:129], v[108:109]
	v_cvt_pk_bf16_f32 v108, v116, v117
	v_mul_f32_e32 v116, 0x4b800000, v172
	v_cndmask_b32_e32 v116, v172, v116, vcc
	v_rsq_f32_e32 v116, v116
	v_pk_mul_f32 v[118:119], v[134:135], v[118:119]
	v_cvt_pk_bf16_f32 v110, v110, v111
	v_cvt_pk_bf16_f32 v109, v118, v119
	v_cvt_pk_bf16_f32 v111, v120, v121
	global_store_dwordx4 v[174:175], v[108:111], off offset:64 sc1
	s_nop 1
	v_mul_f32_e32 v108, 0x45800000, v116
	v_cndmask_b32_e32 v108, v116, v108, vcc
	v_pk_mul_f32 v[110:111], v[112:113], v[108:109] op_sel_hi:[1,0]
	v_pk_mul_f32 v[112:113], v[114:115], v[108:109] op_sel_hi:[1,0]
	v_pk_mul_f32 v[104:105], v[104:105], v[108:109] op_sel_hi:[1,0]
	v_pk_mul_f32 v[106:107], v[106:107], v[108:109] op_sel_hi:[1,0]
	v_pk_mul_f32 v[112:113], v[142:143], v[112:113]
	v_pk_mul_f32 v[110:111], v[140:141], v[110:111]
	v_pk_mul_f32 v[114:115], v[138:139], v[106:107]
	v_pk_mul_f32 v[106:107], v[136:137], v[104:105]
	v_cvt_pk_bf16_f32 v104, v110, v111
	v_cvt_pk_bf16_f32 v105, v112, v113
	v_cvt_pk_bf16_f32 v106, v106, v107
	v_cvt_pk_bf16_f32 v107, v114, v115
	global_store_dwordx4 v[174:175], v[104:107], off offset:2048 sc1
	v_mov_b32_e32 v110, v99
	v_mov_b32_e32 v111, v87
	v_mov_b32_e32 v106, v97
	v_mov_b32_e32 v107, v85
	v_mov_b32_e32 v104, v96
	v_mov_b32_e32 v105, v84
	v_pk_mul_f32 v[106:107], v[106:107], v[106:107]
	v_pk_mul_f32 v[110:111], v[110:111], v[110:111]
	v_pk_fma_f32 v[104:105], v[104:105], v[104:105], v[106:107]
	v_mov_b32_e32 v106, v98
	v_mov_b32_e32 v107, v86
	v_pk_fma_f32 v[106:107], v[106:107], v[106:107], v[110:111]
	v_mov_b32_e32 v110, v89
	v_mov_b32_e32 v111, v77
	v_pk_add_f32 v[104:105], v[104:105], v[106:107]
	v_mov_b32_e32 v106, v88
	v_mov_b32_e32 v107, v76
	v_pk_mul_f32 v[110:111], v[110:111], v[110:111]
	v_mov_b32_e32 v112, v91
	v_mov_b32_e32 v113, v79
	v_pk_fma_f32 v[106:107], v[106:107], v[106:107], v[110:111]
	v_mov_b32_e32 v110, v90
	v_mov_b32_e32 v111, v78
	v_pk_mul_f32 v[112:113], v[112:113], v[112:113]
	v_mov_b32_e32 v114, v75
	v_pk_fma_f32 v[110:111], v[110:111], v[110:111], v[112:113]
	v_mov_b32_e32 v112, v83
	v_pk_add_f32 v[106:107], v[106:107], v[110:111]
	v_mov_b32_e32 v110, v81
	v_mov_b32_e32 v111, v69
	v_pk_add_f32 v[104:105], v[104:105], v[106:107]
	v_mov_b32_e32 v106, v80
	v_mov_b32_e32 v107, v68
	v_pk_mul_f32 v[110:111], v[110:111], v[110:111]
	v_mov_b32_e32 v113, v71
	v_pk_fma_f32 v[106:107], v[106:107], v[106:107], v[110:111]
	v_mov_b32_e32 v110, v82
	v_mov_b32_e32 v111, v70
	v_pk_mul_f32 v[112:113], v[112:113], v[112:113]
	v_mov_b32_e32 v115, v67
	v_pk_fma_f32 v[110:111], v[110:111], v[110:111], v[112:113]
	v_mov_b32_e32 v112, v73
	v_mov_b32_e32 v113, v65
	v_pk_add_f32 v[106:107], v[106:107], v[110:111]
	v_mov_b32_e32 v110, v72
	v_mov_b32_e32 v111, v64
	v_pk_mul_f32 v[112:113], v[112:113], v[112:113]
	v_pk_mul_f32 v[114:115], v[114:115], v[114:115]
	v_pk_fma_f32 v[110:111], v[110:111], v[110:111], v[112:113]
	v_mov_b32_e32 v112, v74
	v_mov_b32_e32 v113, v66
	v_pk_fma_f32 v[112:113], v[112:113], v[112:113], v[114:115]
	v_pk_mul_f32 v[100:101], v[100:101], v[108:109] op_sel_hi:[1,0]
	v_pk_add_f32 v[110:111], v[110:111], v[112:113]
	v_pk_mul_f32 v[100:101], v[132:133], v[100:101]
	v_pk_add_f32 v[106:107], v[106:107], v[110:111]
	v_mov_b32_e32 v111, v104
	v_mov_b32_e32 v110, v106
	v_mov_b32_e32 v104, v107
	v_pk_add_f32 v[104:105], v[110:111], v[104:105]
	ds_bpermute_b32 v107, v171, v105
	ds_bpermute_b32 v106, v171, v104
	v_pk_mul_f32 v[92:93], v[92:93], v[108:109] op_sel_hi:[1,0]
	v_pk_mul_f32 v[94:95], v[94:95], v[108:109] op_sel_hi:[1,0]
	v_pk_mul_f32 v[102:103], v[102:103], v[108:109] op_sel_hi:[1,0]
	v_pk_mul_f32 v[108:109], v[130:131], v[94:95]
	s_waitcnt lgkmcnt(0)
	v_pk_add_f32 v[104:105], v[104:105], v[106:107]
	ds_bpermute_b32 v107, v170, v105
	ds_bpermute_b32 v106, v170, v104
	v_pk_mul_f32 v[94:95], v[128:129], v[92:93]
	v_cvt_pk_bf16_f32 v92, v100, v101
	v_pk_mul_f32 v[102:103], v[134:135], v[102:103]
	v_cvt_pk_bf16_f32 v94, v94, v95
	s_waitcnt lgkmcnt(0)
	v_pk_add_f32 v[100:101], v[104:105], v[106:107]
	v_cvt_pk_bf16_f32 v93, v102, v103
	v_pk_fma_f32 v[100:101], v[100:101], s[48:49], v[158:159] op_sel_hi:[1,0,0]
	v_cvt_pk_bf16_f32 v95, v108, v109
	v_mul_f32_e32 v102, 0x4b800000, v101
	v_cmp_gt_f32_e32 vcc, s86, v101
	global_store_dwordx4 v[174:175], v[92:95], off offset:2112 sc1
	s_nop 0
	v_cndmask_b32_e32 v101, v101, v102, vcc
	v_rsq_f32_e32 v101, v101
	s_nop 0
	v_mul_f32_e32 v92, 0x45800000, v101
	v_cndmask_b32_e32 v92, v101, v92, vcc
	v_pk_mul_f32 v[94:95], v[96:97], v[92:93] op_sel_hi:[1,0]
	v_pk_mul_f32 v[96:97], v[98:99], v[92:93] op_sel_hi:[1,0]
	v_pk_mul_f32 v[94:95], v[140:141], v[94:95]
	v_pk_mul_f32 v[88:89], v[88:89], v[92:93] op_sel_hi:[1,0]
	v_pk_mul_f32 v[90:91], v[90:91], v[92:93] op_sel_hi:[1,0]
	v_pk_mul_f32 v[96:97], v[142:143], v[96:97]
	v_pk_mul_f32 v[98:99], v[138:139], v[90:91]
	v_pk_mul_f32 v[90:91], v[136:137], v[88:89]
	v_cvt_pk_bf16_f32 v88, v94, v95
	v_add_co_u32_e32 v94, vcc, s87, v174
	v_pk_mul_f32 v[84:85], v[84:85], v[92:93] op_sel_hi:[1,0]
	v_cvt_pk_bf16_f32 v89, v96, v97
	v_cvt_pk_bf16_f32 v90, v90, v91
	v_cvt_pk_bf16_f32 v91, v98, v99
	v_addc_co_u32_e32 v95, vcc, 0, v175, vcc
	v_pk_mul_f32 v[84:85], v[132:133], v[84:85]
	v_pk_mul_f32 v[76:77], v[76:77], v[92:93] op_sel_hi:[1,0]
	v_pk_mul_f32 v[78:79], v[78:79], v[92:93] op_sel_hi:[1,0]
	global_store_dwordx4 v[94:95], v[88:91], off sc1
	v_cmp_gt_f32_e32 vcc, s86, v100
	v_pk_mul_f32 v[86:87], v[86:87], v[92:93] op_sel_hi:[1,0]
	v_pk_mul_f32 v[88:89], v[130:131], v[78:79]
	v_pk_mul_f32 v[78:79], v[128:129], v[76:77]
	v_cvt_pk_bf16_f32 v76, v84, v85
	v_mul_f32_e32 v84, 0x4b800000, v100
	v_cndmask_b32_e32 v84, v100, v84, vcc
	v_rsq_f32_e32 v84, v84
	v_pk_mul_f32 v[86:87], v[134:135], v[86:87]
	v_cvt_pk_bf16_f32 v78, v78, v79
	v_cvt_pk_bf16_f32 v77, v86, v87
	v_cvt_pk_bf16_f32 v79, v88, v89
	global_store_dwordx4 v[94:95], v[76:79], off offset:64 sc1
	s_nop 1
	v_mul_f32_e32 v76, 0x45800000, v84
	v_cndmask_b32_e32 v76, v84, v76, vcc
	v_pk_mul_f32 v[78:79], v[80:81], v[76:77] op_sel_hi:[1,0]
	v_pk_mul_f32 v[80:81], v[82:83], v[76:77] op_sel_hi:[1,0]
	v_pk_mul_f32 v[72:73], v[72:73], v[76:77] op_sel_hi:[1,0]
	v_pk_mul_f32 v[74:75], v[74:75], v[76:77] op_sel_hi:[1,0]
	v_pk_mul_f32 v[80:81], v[142:143], v[80:81]
	v_pk_mul_f32 v[78:79], v[140:141], v[78:79]
	v_pk_mul_f32 v[82:83], v[138:139], v[74:75]
	v_pk_mul_f32 v[74:75], v[136:137], v[72:73]
	v_pk_mul_f32 v[70:71], v[70:71], v[76:77] op_sel_hi:[1,0]
	v_cvt_pk_bf16_f32 v72, v78, v79
	v_cvt_pk_bf16_f32 v73, v80, v81
	v_cvt_pk_bf16_f32 v74, v74, v75
	v_cvt_pk_bf16_f32 v75, v82, v83
	v_pk_mul_f32 v[68:69], v[68:69], v[76:77] op_sel_hi:[1,0]
	v_pk_mul_f32 v[70:71], v[134:135], v[70:71]
	v_pk_mul_f32 v[64:65], v[64:65], v[76:77] op_sel_hi:[1,0]
	v_pk_mul_f32 v[66:67], v[66:67], v[76:77] op_sel_hi:[1,0]
	global_store_dwordx4 v[94:95], v[72:75], off offset:2048 sc1
	v_pk_mul_f32 v[68:69], v[132:133], v[68:69]
	v_mov_b32_e32 v76, v59
	v_pk_mul_f32 v[72:73], v[130:131], v[66:67]
	v_pk_mul_f32 v[66:67], v[128:129], v[64:65]
	v_cvt_pk_bf16_f32 v65, v70, v71
	v_mov_b32_e32 v70, v61
	v_mov_b32_e32 v71, v53
	v_cvt_pk_bf16_f32 v64, v68, v69
	v_mov_b32_e32 v68, v60
	v_mov_b32_e32 v69, v52
	v_pk_mul_f32 v[70:71], v[70:71], v[70:71]
	v_mov_b32_e32 v74, v63
	v_mov_b32_e32 v75, v55
	v_pk_fma_f32 v[68:69], v[68:69], v[68:69], v[70:71]
	v_mov_b32_e32 v70, v62
	v_mov_b32_e32 v71, v54
	v_pk_mul_f32 v[74:75], v[74:75], v[74:75]
	v_mov_b32_e32 v77, v47
	v_pk_fma_f32 v[70:71], v[70:71], v[70:71], v[74:75]
	v_mov_b32_e32 v74, v57
	v_mov_b32_e32 v75, v45
	v_pk_add_f32 v[68:69], v[68:69], v[70:71]
	v_mov_b32_e32 v70, v56
	v_mov_b32_e32 v71, v44
	v_pk_mul_f32 v[74:75], v[74:75], v[74:75]
	v_pk_mul_f32 v[76:77], v[76:77], v[76:77]
	v_pk_fma_f32 v[70:71], v[70:71], v[70:71], v[74:75]
	v_mov_b32_e32 v74, v58
	v_mov_b32_e32 v75, v46
	v_pk_fma_f32 v[74:75], v[74:75], v[74:75], v[76:77]
	v_mov_b32_e32 v76, v51
	v_pk_add_f32 v[70:71], v[70:71], v[74:75]
	v_mov_b32_e32 v74, v49
	v_mov_b32_e32 v75, v37
	v_pk_add_f32 v[68:69], v[68:69], v[70:71]
	v_mov_b32_e32 v70, v48
	v_mov_b32_e32 v71, v36
	v_pk_mul_f32 v[74:75], v[74:75], v[74:75]
	v_mov_b32_e32 v77, v39
	v_pk_fma_f32 v[70:71], v[70:71], v[70:71], v[74:75]
	v_mov_b32_e32 v74, v50
	v_mov_b32_e32 v75, v38
	v_pk_mul_f32 v[76:77], v[76:77], v[76:77]
	v_mov_b32_e32 v78, v43
	v_pk_fma_f32 v[74:75], v[74:75], v[74:75], v[76:77]
	v_mov_b32_e32 v76, v41
	v_mov_b32_e32 v77, v29
	v_pk_add_f32 v[70:71], v[70:71], v[74:75]
	v_mov_b32_e32 v74, v40
	v_mov_b32_e32 v75, v28
	v_pk_mul_f32 v[76:77], v[76:77], v[76:77]
	v_mov_b32_e32 v79, v31
	v_pk_fma_f32 v[74:75], v[74:75], v[74:75], v[76:77]
	v_mov_b32_e32 v76, v42
	v_mov_b32_e32 v77, v30
	v_pk_mul_f32 v[78:79], v[78:79], v[78:79]
	v_cvt_pk_bf16_f32 v66, v66, v67
	v_pk_fma_f32 v[76:77], v[76:77], v[76:77], v[78:79]
	v_cvt_pk_bf16_f32 v67, v72, v73
	v_pk_add_f32 v[74:75], v[74:75], v[76:77]
	global_store_dwordx4 v[94:95], v[64:67], off offset:2112 sc1
	v_pk_add_f32 v[70:71], v[70:71], v[74:75]
	v_mov_b32_e32 v75, v68
	v_mov_b32_e32 v74, v70
	v_mov_b32_e32 v68, v71
	v_pk_add_f32 v[68:69], v[74:75], v[68:69]
	ds_bpermute_b32 v71, v171, v69
	ds_bpermute_b32 v70, v171, v68
	v_add_u32_e32 v72, 0x80, v169
	v_ashrrev_i32_e32 v73, 10, v72
	s_waitcnt lgkmcnt(0)
	v_pk_add_f32 v[64:65], v[68:69], v[70:71]
	ds_bpermute_b32 v67, v170, v65
	ds_bpermute_b32 v66, v170, v64
	v_bfi_b32 v68, -8, v73, s57
	v_ashrrev_i32_e32 v69, 31, v68
	v_lshlrev_b64 v[68:69], 20, v[68:69]
	v_lshl_add_u64 v[68:69], v[160:161], 0, v[68:69]
	s_waitcnt lgkmcnt(0)
	v_pk_add_f32 v[64:65], v[64:65], v[66:67]
	s_nop 0
	v_pk_fma_f32 v[64:65], v[64:65], s[48:49], v[158:159] op_sel_hi:[1,0,0]
	s_nop 0
	v_mul_f32_e32 v66, 0x4b800000, v65
	v_cmp_gt_f32_e32 vcc, s86, v65
	s_nop 1
	v_cndmask_b32_e32 v65, v65, v66, vcc
	v_rsq_f32_e32 v65, v65
	v_lshlrev_b32_e32 v66, 7, v72
	v_and_b32_e32 v148, 0xfe780, v66
	v_lshl_add_u64 v[66:67], v[68:69], 0, v[148:149]
	v_mul_f32_e32 v68, 0x45800000, v65
	v_cndmask_b32_e32 v68, v65, v68, vcc
	v_pk_mul_f32 v[60:61], v[60:61], v[68:69] op_sel_hi:[1,0]
	v_pk_mul_f32 v[62:63], v[62:63], v[68:69] op_sel_hi:[1,0]
	v_pk_mul_f32 v[56:57], v[56:57], v[68:69] op_sel_hi:[1,0]
	v_pk_mul_f32 v[58:59], v[58:59], v[68:69] op_sel_hi:[1,0]
	v_pk_mul_f32 v[62:63], v[142:143], v[62:63]
	v_pk_mul_f32 v[60:61], v[140:141], v[60:61]
	v_pk_mul_f32 v[70:71], v[138:139], v[58:59]
	v_pk_mul_f32 v[58:59], v[136:137], v[56:57]
	v_pk_mul_f32 v[52:53], v[52:53], v[68:69] op_sel_hi:[1,0]
	v_cvt_pk_bf16_f32 v56, v60, v61
	v_cvt_pk_bf16_f32 v57, v62, v63
	v_cvt_pk_bf16_f32 v58, v58, v59
	v_cvt_pk_bf16_f32 v59, v70, v71
	v_pk_mul_f32 v[52:53], v[132:133], v[52:53]
	v_pk_mul_f32 v[44:45], v[44:45], v[68:69] op_sel_hi:[1,0]
	v_pk_mul_f32 v[46:47], v[46:47], v[68:69] op_sel_hi:[1,0]
	global_store_dwordx4 v[66:67], v[56:59], off sc1
	v_cmp_gt_f32_e32 vcc, s86, v64
	v_pk_mul_f32 v[54:55], v[54:55], v[68:69] op_sel_hi:[1,0]
	v_pk_mul_f32 v[56:57], v[130:131], v[46:47]
	v_pk_mul_f32 v[46:47], v[128:129], v[44:45]
	v_cvt_pk_bf16_f32 v44, v52, v53
	v_mul_f32_e32 v52, 0x4b800000, v64
	v_cndmask_b32_e32 v52, v64, v52, vcc
	v_rsq_f32_e32 v52, v52
	v_pk_mul_f32 v[54:55], v[134:135], v[54:55]
	v_cvt_pk_bf16_f32 v46, v46, v47
	v_cvt_pk_bf16_f32 v45, v54, v55
	v_cvt_pk_bf16_f32 v47, v56, v57
	global_store_dwordx4 v[66:67], v[44:47], off offset:64 sc1
	s_nop 1
	v_mul_f32_e32 v44, 0x45800000, v52
	v_cndmask_b32_e32 v44, v52, v44, vcc
	v_pk_mul_f32 v[46:47], v[48:49], v[44:45] op_sel_hi:[1,0]
	v_pk_mul_f32 v[48:49], v[50:51], v[44:45] op_sel_hi:[1,0]
	v_pk_mul_f32 v[40:41], v[40:41], v[44:45] op_sel_hi:[1,0]
	v_pk_mul_f32 v[42:43], v[42:43], v[44:45] op_sel_hi:[1,0]
	v_pk_mul_f32 v[48:49], v[142:143], v[48:49]
	v_pk_mul_f32 v[46:47], v[140:141], v[46:47]
	v_pk_mul_f32 v[50:51], v[138:139], v[42:43]
	v_pk_mul_f32 v[42:43], v[136:137], v[40:41]
	v_cvt_pk_bf16_f32 v40, v46, v47
	v_cvt_pk_bf16_f32 v41, v48, v49
	v_cvt_pk_bf16_f32 v42, v42, v43
	v_cvt_pk_bf16_f32 v43, v50, v51
	global_store_dwordx4 v[66:67], v[40:43], off offset:2048 sc1
	v_mov_b32_e32 v46, v35
	v_mov_b32_e32 v47, v23
	v_mov_b32_e32 v42, v33
	v_mov_b32_e32 v43, v21
	v_mov_b32_e32 v40, v32
	v_mov_b32_e32 v41, v20
	v_pk_mul_f32 v[42:43], v[42:43], v[42:43]
	v_pk_mul_f32 v[46:47], v[46:47], v[46:47]
	v_pk_fma_f32 v[40:41], v[40:41], v[40:41], v[42:43]
	v_mov_b32_e32 v42, v34
	v_mov_b32_e32 v43, v22
	v_pk_fma_f32 v[42:43], v[42:43], v[42:43], v[46:47]
	v_mov_b32_e32 v46, v25
	v_mov_b32_e32 v47, v13
	v_pk_add_f32 v[40:41], v[40:41], v[42:43]
	v_mov_b32_e32 v42, v24
	v_mov_b32_e32 v43, v12
	v_pk_mul_f32 v[46:47], v[46:47], v[46:47]
	v_mov_b32_e32 v48, v27
	v_mov_b32_e32 v49, v15
	v_pk_fma_f32 v[42:43], v[42:43], v[42:43], v[46:47]
	v_mov_b32_e32 v46, v26
	v_mov_b32_e32 v47, v14
	v_pk_mul_f32 v[48:49], v[48:49], v[48:49]
	v_mov_b32_e32 v50, v11
	v_pk_fma_f32 v[46:47], v[46:47], v[46:47], v[48:49]
	v_mov_b32_e32 v48, v19
	v_pk_add_f32 v[42:43], v[42:43], v[46:47]
	v_mov_b32_e32 v46, v17
	v_mov_b32_e32 v47, v5
	v_pk_add_f32 v[40:41], v[40:41], v[42:43]
	v_mov_b32_e32 v42, v16
	v_mov_b32_e32 v43, v4
	v_pk_mul_f32 v[46:47], v[46:47], v[46:47]
	v_mov_b32_e32 v49, v7
	v_pk_fma_f32 v[42:43], v[42:43], v[42:43], v[46:47]
	v_mov_b32_e32 v46, v18
	v_mov_b32_e32 v47, v6
	v_pk_mul_f32 v[48:49], v[48:49], v[48:49]
	v_mov_b32_e32 v51, v3
	v_pk_fma_f32 v[46:47], v[46:47], v[46:47], v[48:49]
	v_mov_b32_e32 v48, v9
	v_mov_b32_e32 v49, v1
	v_pk_add_f32 v[42:43], v[42:43], v[46:47]
	v_mov_b32_e32 v46, v8
	v_mov_b32_e32 v47, v0
	v_pk_mul_f32 v[48:49], v[48:49], v[48:49]
	v_pk_mul_f32 v[50:51], v[50:51], v[50:51]
	v_pk_fma_f32 v[46:47], v[46:47], v[46:47], v[48:49]
	v_mov_b32_e32 v48, v10
	v_mov_b32_e32 v49, v2
	v_pk_fma_f32 v[48:49], v[48:49], v[48:49], v[50:51]
	v_pk_mul_f32 v[36:37], v[36:37], v[44:45] op_sel_hi:[1,0]
	v_pk_add_f32 v[46:47], v[46:47], v[48:49]
	v_pk_mul_f32 v[36:37], v[132:133], v[36:37]
	v_pk_add_f32 v[42:43], v[42:43], v[46:47]
	v_mov_b32_e32 v47, v40
	v_mov_b32_e32 v46, v42
	v_mov_b32_e32 v40, v43
	v_pk_add_f32 v[40:41], v[46:47], v[40:41]
	ds_bpermute_b32 v43, v171, v41
	ds_bpermute_b32 v42, v171, v40
	v_pk_mul_f32 v[28:29], v[28:29], v[44:45] op_sel_hi:[1,0]
	v_pk_mul_f32 v[30:31], v[30:31], v[44:45] op_sel_hi:[1,0]
	v_pk_mul_f32 v[38:39], v[38:39], v[44:45] op_sel_hi:[1,0]
	v_pk_mul_f32 v[44:45], v[130:131], v[30:31]
	s_waitcnt lgkmcnt(0)
	v_pk_add_f32 v[40:41], v[40:41], v[42:43]
	ds_bpermute_b32 v43, v170, v41
	ds_bpermute_b32 v42, v170, v40
	v_pk_mul_f32 v[30:31], v[128:129], v[28:29]
	v_cvt_pk_bf16_f32 v28, v36, v37
	v_pk_mul_f32 v[38:39], v[134:135], v[38:39]
	v_cvt_pk_bf16_f32 v30, v30, v31
	s_waitcnt lgkmcnt(0)
	v_pk_add_f32 v[36:37], v[40:41], v[42:43]
	v_cvt_pk_bf16_f32 v29, v38, v39
	v_pk_fma_f32 v[36:37], v[36:37], s[48:49], v[158:159] op_sel_hi:[1,0,0]
	v_cvt_pk_bf16_f32 v31, v44, v45
	v_mul_f32_e32 v38, 0x4b800000, v37
	v_cmp_gt_f32_e32 vcc, s86, v37
	global_store_dwordx4 v[66:67], v[28:31], off offset:2112 sc1
	s_nop 0
	v_cndmask_b32_e32 v37, v37, v38, vcc
	v_rsq_f32_e32 v37, v37
	s_nop 0
	v_mul_f32_e32 v28, 0x45800000, v37
	v_cndmask_b32_e32 v28, v37, v28, vcc
	v_pk_mul_f32 v[30:31], v[32:33], v[28:29] op_sel_hi:[1,0]
	v_pk_mul_f32 v[32:33], v[34:35], v[28:29] op_sel_hi:[1,0]
	v_pk_mul_f32 v[30:31], v[140:141], v[30:31]
	v_pk_mul_f32 v[24:25], v[24:25], v[28:29] op_sel_hi:[1,0]
	v_pk_mul_f32 v[26:27], v[26:27], v[28:29] op_sel_hi:[1,0]
	v_pk_mul_f32 v[32:33], v[142:143], v[32:33]
	v_pk_mul_f32 v[34:35], v[138:139], v[26:27]
	v_pk_mul_f32 v[26:27], v[136:137], v[24:25]
	v_cvt_pk_bf16_f32 v24, v30, v31
	v_add_co_u32_e32 v30, vcc, s87, v66
	v_pk_mul_f32 v[20:21], v[20:21], v[28:29] op_sel_hi:[1,0]
	v_cvt_pk_bf16_f32 v25, v32, v33
	v_cvt_pk_bf16_f32 v26, v26, v27
	v_cvt_pk_bf16_f32 v27, v34, v35
	v_addc_co_u32_e32 v31, vcc, 0, v67, vcc
	v_pk_mul_f32 v[20:21], v[132:133], v[20:21]
	v_pk_mul_f32 v[12:13], v[12:13], v[28:29] op_sel_hi:[1,0]
	v_pk_mul_f32 v[14:15], v[14:15], v[28:29] op_sel_hi:[1,0]
	global_store_dwordx4 v[30:31], v[24:27], off sc1
	v_cmp_gt_f32_e32 vcc, s86, v36
	v_pk_mul_f32 v[22:23], v[22:23], v[28:29] op_sel_hi:[1,0]
	v_pk_mul_f32 v[24:25], v[130:131], v[14:15]
	v_pk_mul_f32 v[14:15], v[128:129], v[12:13]
	v_cvt_pk_bf16_f32 v12, v20, v21
	v_mul_f32_e32 v20, 0x4b800000, v36
	v_cndmask_b32_e32 v20, v36, v20, vcc
	v_rsq_f32_e32 v20, v20
	v_pk_mul_f32 v[22:23], v[134:135], v[22:23]
	v_cvt_pk_bf16_f32 v14, v14, v15
	v_cvt_pk_bf16_f32 v13, v22, v23
	v_cvt_pk_bf16_f32 v15, v24, v25
	global_store_dwordx4 v[30:31], v[12:15], off offset:64 sc1
	s_nop 1
	v_mul_f32_e32 v12, 0x45800000, v20
	v_cndmask_b32_e32 v12, v20, v12, vcc
	v_pk_mul_f32 v[14:15], v[16:17], v[12:13] op_sel_hi:[1,0]
	v_pk_mul_f32 v[16:17], v[18:19], v[12:13] op_sel_hi:[1,0]
	v_pk_mul_f32 v[8:9], v[8:9], v[12:13] op_sel_hi:[1,0]
	v_pk_mul_f32 v[10:11], v[10:11], v[12:13] op_sel_hi:[1,0]
	v_pk_mul_f32 v[16:17], v[142:143], v[16:17]
	v_pk_mul_f32 v[14:15], v[140:141], v[14:15]
	v_pk_mul_f32 v[18:19], v[138:139], v[10:11]
	v_pk_mul_f32 v[10:11], v[136:137], v[8:9]
	v_cvt_pk_bf16_f32 v8, v14, v15
	v_cvt_pk_bf16_f32 v9, v16, v17
	v_cvt_pk_bf16_f32 v10, v10, v11
	v_cvt_pk_bf16_f32 v11, v18, v19
	v_pk_mul_f32 v[4:5], v[4:5], v[12:13] op_sel_hi:[1,0]
	v_pk_mul_f32 v[6:7], v[6:7], v[12:13] op_sel_hi:[1,0]
	v_pk_mul_f32 v[0:1], v[0:1], v[12:13] op_sel_hi:[1,0]
	v_pk_mul_f32 v[2:3], v[2:3], v[12:13] op_sel_hi:[1,0]
	global_store_dwordx4 v[30:31], v[8:11], off offset:2048 sc1
	v_pk_mul_f32 v[6:7], v[134:135], v[6:7]
	v_pk_mul_f32 v[4:5], v[132:133], v[4:5]
	v_pk_mul_f32 v[8:9], v[130:131], v[2:3]
	v_pk_mul_f32 v[2:3], v[128:129], v[0:1]
	v_cvt_pk_bf16_f32 v0, v4, v5
	v_cvt_pk_bf16_f32 v1, v6, v7
	v_cvt_pk_bf16_f32 v2, v2, v3
	v_cvt_pk_bf16_f32 v3, v8, v9
	global_store_dwordx4 v[30:31], v[0:3], off offset:2112 sc1
